# zeroing with 64-bit moves also in the FFN-down and ple-gate GEMM instances
# speedup vs baseline: 1.0853x; 1.0012x over previous
; template <class Epi, class Sched, bool ALIGN_EPI = false, bool SP2 = false>
; __device__ __forceinline__ void gemm_phase(PG8_LAS unsigned char* lds, const Gemm g, const Sched& S, const Epi& E) {
;     ...
; #pragma unroll
;         for (int a = 0; a < 2; ++a)
; #pragma unroll
;             for (int b = 0; b < 2; ++b)
; #pragma unroll
;                 for (int m = 0; m < 4; ++m)
; #pragma unroll
;                     for (int n = 0; n < 2; ++n) acc[a][b][m][n] = (f32x4){0.f, 0.f, 0.f, 0.f};
.LBB0_366:
	v_mov_b64_e32 v[64:65], 0
	v_mov_b64_e32 v[66:67], 0
	v_mov_b64_e32 v[68:69], 0
	v_mov_b64_e32 v[70:71], 0
	v_mov_b64_e32 v[72:73], 0
	v_mov_b64_e32 v[74:75], 0
	v_mov_b64_e32 v[76:77], 0
	v_mov_b64_e32 v[78:79], 0
	v_mov_b64_e32 v[80:81], 0
	v_mov_b64_e32 v[82:83], 0
	v_mov_b64_e32 v[84:85], 0
	v_mov_b64_e32 v[86:87], 0
	v_mov_b64_e32 v[88:89], 0
	v_mov_b64_e32 v[90:91], 0
	v_mov_b64_e32 v[92:93], 0
	v_mov_b64_e32 v[94:95], 0
	v_mov_b64_e32 v[96:97], 0
	v_mov_b64_e32 v[98:99], 0
	v_mov_b64_e32 v[100:101], 0
	v_mov_b64_e32 v[102:103], 0
	v_mov_b64_e32 v[104:105], 0
	v_mov_b64_e32 v[106:107], 0
	v_mov_b64_e32 v[108:109], 0
	v_mov_b64_e32 v[110:111], 0
	v_mov_b64_e32 v[112:113], 0
	v_mov_b64_e32 v[114:115], 0
	v_mov_b64_e32 v[116:117], 0
	v_mov_b64_e32 v[118:119], 0
	v_mov_b64_e32 v[120:121], 0
	v_mov_b64_e32 v[122:123], 0
	v_mov_b64_e32 v[124:125], 0
	v_mov_b64_e32 v[126:127], 0
	v_mov_b64_e32 v[144:145], 0
	v_mov_b64_e32 v[146:147], 0
	v_mov_b64_e32 v[148:149], 0
	v_mov_b64_e32 v[150:151], 0
	v_mov_b64_e32 v[154:155], 0
	v_mov_b64_e32 v[156:157], 0
	v_mov_b64_e32 v[158:159], 0
	v_mov_b64_e32 v[160:161], 0
	v_mov_b64_e32 v[164:165], 0
	v_mov_b64_e32 v[166:167], 0
	v_mov_b64_e32 v[168:169], 0
	v_mov_b64_e32 v[170:171], 0
	v_mov_b64_e32 v[172:173], 0
	v_mov_b64_e32 v[174:175], 0
	v_mov_b64_e32 v[176:177], 0
	v_mov_b64_e32 v[178:179], 0
	v_mov_b64_e32 v[184:185], 0
	v_mov_b64_e32 v[186:187], 0
	v_mov_b64_e32 v[188:189], 0
	v_mov_b64_e32 v[190:191], 0
	v_mov_b64_e32 v[194:195], 0
	v_mov_b64_e32 v[196:197], 0
	v_mov_b64_e32 v[198:199], 0
	v_mov_b64_e32 v[200:201], 0
	v_mov_b64_e32 v[208:209], 0
	v_mov_b64_e32 v[212:213], 0
	v_mov_b64_e32 v[214:215], 0
	v_mov_b64_e32 v[216:217], 0
	v_mov_b64_e32 v[222:223], 0
	v_mov_b64_e32 v[224:225], 0
	v_mov_b64_e32 v[226:227], 0
	v_mov_b64_e32 v[228:229], 0
	s_andn2_b64 vcc, exec, s[40:41]
	.p2align 8
	s_cbranch_vccnz .LBB0_370
	s_add_u32 s58, s58, 0x80
	s_addc_u32 s59, s59, 0
	s_add_u32 s4, s60, 0x100
	v_mov_b64_e32 v[0:1], 0
	v_mov_b64_e32 v[2:3], 0
	v_mov_b64_e32 v[4:5], 0
	v_mov_b64_e32 v[6:7], 0
	v_mov_b64_e32 v[8:9], 0
	v_mov_b64_e32 v[10:11], 0
	v_mov_b64_e32 v[12:13], 0
	v_mov_b64_e32 v[14:15], 0
	v_mov_b64_e32 v[16:17], 0
	v_mov_b64_e32 v[18:19], 0
	v_mov_b64_e32 v[20:21], 0
	v_mov_b64_e32 v[22:23], 0
	v_mov_b64_e32 v[24:25], 0
	v_mov_b64_e32 v[26:27], 0
	v_mov_b64_e32 v[28:29], 0
	v_mov_b64_e32 v[30:31], 0
	v_mov_b64_e32 v[32:33], 0
	v_mov_b64_e32 v[34:35], 0
	v_mov_b64_e32 v[36:37], 0
	v_mov_b64_e32 v[38:39], 0
	v_mov_b64_e32 v[40:41], 0
	v_mov_b64_e32 v[42:43], 0
	v_mov_b64_e32 v[44:45], 0
	v_mov_b64_e32 v[46:47], 0
	v_mov_b64_e32 v[48:49], 0
	v_mov_b64_e32 v[50:51], 0
	v_mov_b64_e32 v[52:53], 0
	v_mov_b64_e32 v[54:55], 0
	v_mov_b64_e32 v[56:57], 0
	v_mov_b64_e32 v[58:59], 0
	v_mov_b64_e32 v[60:61], 0
	v_mov_b64_e32 v[62:63], 0
	v_mov_b64_e32 v[64:65], 0
	v_mov_b64_e32 v[66:67], 0
	v_mov_b64_e32 v[68:69], 0
	v_mov_b64_e32 v[70:71], 0
	v_mov_b64_e32 v[72:73], 0
	v_mov_b64_e32 v[74:75], 0
	v_mov_b64_e32 v[76:77], 0
	v_mov_b64_e32 v[78:79], 0
	v_mov_b64_e32 v[80:81], 0
	v_mov_b64_e32 v[82:83], 0
	v_mov_b64_e32 v[84:85], 0
	v_mov_b64_e32 v[86:87], 0
	v_mov_b64_e32 v[88:89], 0
	v_mov_b64_e32 v[90:91], 0
	v_mov_b64_e32 v[92:93], 0
	v_mov_b64_e32 v[94:95], 0
	v_mov_b64_e32 v[96:97], 0
	v_mov_b64_e32 v[98:99], 0
	v_mov_b64_e32 v[100:101], 0
	v_mov_b64_e32 v[102:103], 0
	v_mov_b64_e32 v[104:105], 0
	v_mov_b64_e32 v[106:107], 0
	v_mov_b64_e32 v[108:109], 0
	v_mov_b64_e32 v[110:111], 0
	v_mov_b64_e32 v[112:113], 0
	v_mov_b64_e32 v[114:115], 0
	v_mov_b64_e32 v[116:117], 0
	v_mov_b64_e32 v[118:119], 0
	v_mov_b64_e32 v[120:121], 0
	v_mov_b64_e32 v[122:123], 0
	v_mov_b64_e32 v[124:125], 0
	v_mov_b64_e32 v[126:127], 0
	s_addc_u32 s5, s61, 0
	s_mov_b32 s33, 0
	s_waitcnt lgkmcnt(0)
	s_waitcnt vmcnt(0)

; template <class Epi, class Sched, bool ALIGN_EPI = false, bool SP2 = false>
; __device__ __forceinline__ void gemm_phase(PG8_LAS unsigned char* lds, const Gemm g, const Sched& S, const Epi& E) {
;     ...
; #pragma unroll
;         for (int a = 0; a < 2; ++a)
; #pragma unroll
;             for (int b = 0; b < 2; ++b)
; #pragma unroll
;                 for (int m = 0; m < 4; ++m)
; #pragma unroll
;                     for (int n = 0; n < 2; ++n) acc[a][b][m][n] = (f32x4){0.f, 0.f, 0.f, 0.f};
.LBB0_1116:
	v_mov_b64_e32 v[64:65], 0
	v_mov_b64_e32 v[66:67], 0
	v_mov_b64_e32 v[68:69], 0
	v_mov_b64_e32 v[70:71], 0
	v_mov_b64_e32 v[72:73], 0
	v_mov_b64_e32 v[74:75], 0
	v_mov_b64_e32 v[76:77], 0
	v_mov_b64_e32 v[78:79], 0
	v_mov_b64_e32 v[80:81], 0
	v_mov_b64_e32 v[82:83], 0
	v_mov_b64_e32 v[84:85], 0
	v_mov_b64_e32 v[86:87], 0
	v_mov_b64_e32 v[88:89], 0
	v_mov_b64_e32 v[90:91], 0
	v_mov_b64_e32 v[92:93], 0
	v_mov_b64_e32 v[94:95], 0
	v_mov_b64_e32 v[96:97], 0
	v_mov_b64_e32 v[98:99], 0
	v_mov_b64_e32 v[100:101], 0
	v_mov_b64_e32 v[102:103], 0
	v_mov_b64_e32 v[104:105], 0
	v_mov_b64_e32 v[106:107], 0
	v_mov_b64_e32 v[108:109], 0
	v_mov_b64_e32 v[110:111], 0
	v_mov_b64_e32 v[112:113], 0
	v_mov_b64_e32 v[114:115], 0
	v_mov_b64_e32 v[116:117], 0
	v_mov_b64_e32 v[118:119], 0
	v_mov_b64_e32 v[120:121], 0
	v_mov_b64_e32 v[122:123], 0
	v_mov_b64_e32 v[124:125], 0
	v_mov_b64_e32 v[126:127], 0
	v_mov_b64_e32 v[142:143], 0
	v_mov_b64_e32 v[144:145], 0
	v_mov_b64_e32 v[146:147], 0
	v_mov_b64_e32 v[148:149], 0
	v_mov_b64_e32 v[152:153], 0
	v_mov_b64_e32 v[154:155], 0
	v_mov_b64_e32 v[156:157], 0
	v_mov_b64_e32 v[158:159], 0
	v_mov_b64_e32 v[162:163], 0
	v_mov_b64_e32 v[164:165], 0
	v_mov_b64_e32 v[166:167], 0
	v_mov_b64_e32 v[168:169], 0
	v_mov_b64_e32 v[170:171], 0
	v_mov_b64_e32 v[172:173], 0
	v_mov_b64_e32 v[174:175], 0
	v_mov_b64_e32 v[176:177], 0
	v_mov_b64_e32 v[182:183], 0
	v_mov_b64_e32 v[184:185], 0
	v_mov_b64_e32 v[186:187], 0
	v_mov_b64_e32 v[188:189], 0
	v_mov_b64_e32 v[190:191], 0
	v_mov_b64_e32 v[194:195], 0
	v_mov_b64_e32 v[196:197], 0
	v_mov_b64_e32 v[198:199], 0
	v_mov_b64_e32 v[206:207], 0
	v_mov_b64_e32 v[210:211], 0
	v_mov_b64_e32 v[212:213], 0
	v_mov_b64_e32 v[214:215], 0
	v_mov_b64_e32 v[220:221], 0
	v_mov_b64_e32 v[222:223], 0
	v_mov_b64_e32 v[224:225], 0
	v_mov_b64_e32 v[226:227], 0
	s_andn2_b64 vcc, exec, s[36:37]
	.p2align 8
	s_cbranch_vccnz .LBB0_1120
	s_add_u32 s42, s42, 0x80
	s_addc_u32 s43, s43, 0
	s_add_u32 s4, s54, 0x100
	v_mov_b64_e32 v[0:1], 0
	v_mov_b64_e32 v[2:3], 0
	v_mov_b64_e32 v[4:5], 0
	v_mov_b64_e32 v[6:7], 0
	v_mov_b64_e32 v[8:9], 0
	v_mov_b64_e32 v[10:11], 0
	v_mov_b64_e32 v[12:13], 0
	v_mov_b64_e32 v[14:15], 0
	v_mov_b64_e32 v[16:17], 0
	v_mov_b64_e32 v[18:19], 0
	v_mov_b64_e32 v[20:21], 0
	v_mov_b64_e32 v[22:23], 0
	v_mov_b64_e32 v[24:25], 0
	v_mov_b64_e32 v[26:27], 0
	v_mov_b64_e32 v[28:29], 0
	v_mov_b64_e32 v[30:31], 0
	v_mov_b64_e32 v[32:33], 0
	v_mov_b64_e32 v[34:35], 0
	v_mov_b64_e32 v[36:37], 0
	v_mov_b64_e32 v[38:39], 0
	v_mov_b64_e32 v[40:41], 0
	v_mov_b64_e32 v[42:43], 0
	v_mov_b64_e32 v[44:45], 0
	v_mov_b64_e32 v[46:47], 0
	v_mov_b64_e32 v[48:49], 0
	v_mov_b64_e32 v[50:51], 0
	v_mov_b64_e32 v[52:53], 0
	v_mov_b64_e32 v[54:55], 0
	v_mov_b64_e32 v[56:57], 0
	v_mov_b64_e32 v[58:59], 0
	v_mov_b64_e32 v[60:61], 0
	v_mov_b64_e32 v[62:63], 0
	v_mov_b64_e32 v[64:65], 0
	v_mov_b64_e32 v[66:67], 0
	v_mov_b64_e32 v[68:69], 0
	v_mov_b64_e32 v[70:71], 0
	v_mov_b64_e32 v[72:73], 0
	v_mov_b64_e32 v[74:75], 0
	v_mov_b64_e32 v[76:77], 0
	v_mov_b64_e32 v[78:79], 0
	v_mov_b64_e32 v[80:81], 0
	v_mov_b64_e32 v[82:83], 0
	v_mov_b64_e32 v[84:85], 0
	v_mov_b64_e32 v[86:87], 0
	v_mov_b64_e32 v[88:89], 0
	v_mov_b64_e32 v[90:91], 0
	v_mov_b64_e32 v[92:93], 0
	v_mov_b64_e32 v[94:95], 0
	v_mov_b64_e32 v[96:97], 0
	v_mov_b64_e32 v[98:99], 0
	v_mov_b64_e32 v[100:101], 0
	v_mov_b64_e32 v[102:103], 0
	v_mov_b64_e32 v[104:105], 0
	v_mov_b64_e32 v[106:107], 0
	v_mov_b64_e32 v[108:109], 0
	v_mov_b64_e32 v[110:111], 0
	v_mov_b64_e32 v[112:113], 0
	v_mov_b64_e32 v[114:115], 0
	v_mov_b64_e32 v[116:117], 0
	v_mov_b64_e32 v[118:119], 0
	v_mov_b64_e32 v[120:121], 0
	v_mov_b64_e32 v[122:123], 0
	v_mov_b64_e32 v[124:125], 0
	v_mov_b64_e32 v[126:127], 0
	s_addc_u32 s5, s55, 0
	s_mov_b32 s33, 0
	s_waitcnt vmcnt(0)

; template <class Epi, class Sched, bool ALIGN_EPI = false, bool SP2 = false>
; __device__ __forceinline__ void gemm_phase(PG8_LAS unsigned char* lds, const Gemm g, const Sched& S, const Epi& E) {
;     ...
; #pragma unroll
;         for (int a = 0; a < 2; ++a)
; #pragma unroll
;             for (int b = 0; b < 2; ++b)
; #pragma unroll
;                 for (int m = 0; m < 4; ++m)
; #pragma unroll
;                     for (int n = 0; n < 2; ++n) acc[a][b][m][n] = (f32x4){0.f, 0.f, 0.f, 0.f};
.LBB0_1251:
	v_mov_b64_e32 v[0:1], 0
	v_mov_b64_e32 v[2:3], 0
	v_mov_b64_e32 v[4:5], 0
	v_mov_b64_e32 v[6:7], 0
	v_mov_b64_e32 v[8:9], 0
	v_mov_b64_e32 v[10:11], 0
	v_mov_b64_e32 v[12:13], 0
	v_mov_b64_e32 v[14:15], 0
	v_mov_b64_e32 v[16:17], 0
	v_mov_b64_e32 v[18:19], 0
	v_mov_b64_e32 v[20:21], 0
	v_mov_b64_e32 v[22:23], 0
	v_mov_b64_e32 v[24:25], 0
	v_mov_b64_e32 v[26:27], 0
	v_mov_b64_e32 v[28:29], 0
	v_mov_b64_e32 v[30:31], 0
	v_mov_b64_e32 v[32:33], 0
	v_mov_b64_e32 v[34:35], 0
	v_mov_b64_e32 v[36:37], 0
	v_mov_b64_e32 v[38:39], 0
	v_mov_b64_e32 v[40:41], 0
	v_mov_b64_e32 v[42:43], 0
	v_mov_b64_e32 v[44:45], 0
	v_mov_b64_e32 v[46:47], 0
	v_mov_b64_e32 v[48:49], 0
	v_mov_b64_e32 v[50:51], 0
	v_mov_b64_e32 v[52:53], 0
	v_mov_b64_e32 v[54:55], 0
	v_mov_b64_e32 v[56:57], 0
	v_mov_b64_e32 v[58:59], 0
	v_mov_b64_e32 v[60:61], 0
	v_mov_b64_e32 v[62:63], 0
	v_mov_b64_e32 v[64:65], 0
	v_mov_b64_e32 v[66:67], 0
	v_mov_b64_e32 v[68:69], 0
	v_mov_b64_e32 v[70:71], 0
	v_mov_b64_e32 v[72:73], 0
	v_mov_b64_e32 v[74:75], 0
	v_mov_b64_e32 v[76:77], 0
	v_mov_b64_e32 v[78:79], 0
	v_mov_b64_e32 v[80:81], 0
	v_mov_b64_e32 v[82:83], 0
	v_mov_b64_e32 v[84:85], 0
	v_mov_b64_e32 v[86:87], 0
	v_mov_b64_e32 v[88:89], 0
	v_mov_b64_e32 v[90:91], 0
	v_mov_b64_e32 v[92:93], 0
	v_mov_b64_e32 v[94:95], 0
	v_mov_b64_e32 v[96:97], 0
	v_mov_b64_e32 v[98:99], 0
	v_mov_b64_e32 v[100:101], 0
	v_mov_b64_e32 v[102:103], 0
	v_mov_b64_e32 v[104:105], 0
	v_mov_b64_e32 v[106:107], 0
	v_mov_b64_e32 v[108:109], 0
	v_mov_b64_e32 v[110:111], 0
	v_mov_b64_e32 v[112:113], 0
	v_mov_b64_e32 v[114:115], 0
	v_mov_b64_e32 v[116:117], 0
	v_mov_b64_e32 v[118:119], 0
	v_mov_b64_e32 v[120:121], 0
	v_mov_b64_e32 v[122:123], 0
	v_mov_b64_e32 v[128:129], 0
	v_mov_b64_e32 v[130:131], 0
	s_andn2_b64 vcc, exec, s[16:17]
	.p2align 8
	s_cbranch_vccnz .LBB0_1254
	s_add_u32 s22, s22, 0x80
	s_addc_u32 s23, s23, 0
	s_add_u32 s53, s26, 0x100
	s_addc_u32 s54, s27, 0
	s_mov_b32 s26, 0
